# v16 + GEMM K-loops (UP, IN, residual): back edge rotated - loop-control and next-iteration scalar set-up in front of the closing barrier
# baseline (speedup 1.0000x reference)
; #define PG8_STAGE(bufoff, gbase, voff) do { _Pragma("unroll") for (int _i = 0; _i < 2; ++_i) \
;         __builtin_amdgcn_global_load_lds((const unsigned*)((const char*)(gbase) + (voff)[_i]), (PG8_LAS unsigned*)(lds + (bufoff) + ldsw + _i * 8192), 16, 0, 0); } while (0)
; #define PG8_LDA(dst, b, h) do { _Pragma("unroll") for (int m = 0; m < 4; ++m) _Pragma("unroll") for (int k = 0; k < 2; ++k) dst[m][k] = *(const PG8_LAS bf16x8*)(lds + PG8_SA(b, h) + aoff + m * 2048 + k * 1024); } while (0)
; #define PG8_LDB(dst, b, h) do { _Pragma("unroll") for (int n = 0; n < 2; ++n) _Pragma("unroll") for (int k = 0; k < 2; ++k) dst[n][k] = *(const PG8_LAS bf16x8*)(lds + PG8_SB(b, h) + boff + n * 2048 + k * 1024); } while (0)
; #define PG8_MMA(ai, bj, At, Bt) do { __builtin_amdgcn_s_setprio(1); _Pragma("unroll") for (int m = 0; m < 4; ++m) _Pragma("unroll") for (int n = 0; n < 2; ++n) _Pragma("unroll") for (int k = 0; k < 2; ++k) \
;         acc[ai][bj][m][n] = __builtin_amdgcn_mfma_f32_16x16x32_bf16(Bt[n][k], At[m][k], acc[ai][bj][m][n], 0, 0, 0); __builtin_amdgcn_s_setprio(0); } while (0)
; #define PG8_WAIT_V(n) asm volatile("s_waitcnt vmcnt(" #n ")" ::: "memory")
; #define PG8_WAIT_L(n) asm volatile("s_waitcnt lgkmcnt(" #n ")" ::: "memory")
; #define PG8_BAR __builtin_amdgcn_s_barrier()
; #define PG8_SCHED __builtin_amdgcn_sched_barrier(0)
; template <class Epi, class Sched, bool ALIGN_EPI = false, bool SP2 = false>
; __device__ __forceinline__ void gemm_phase(PG8_LAS unsigned char* lds, const Gemm g, const Sched& S, const Epi& E, const int tid) {
;     ...
;             if constexpr (SP2) {
;             PG8_LDB(B0, 0, 0); PG8_LDB(B1, 0, 1); PG8_SCHED; PG8_LDA(At, 0, 0); PG8_STAGE(PG8_SA(1, 1), a1 + hstep, voffA);
;             PG8_WAIT_V(8); PG8_WAIT_L(0); PG8_BAR; PG8_MMA(0, 0, At, B0); PG8_MMA(0, 1, At, B1); PG8_BAR; PG8_SCHED;
;             PG8_LDA(At, 0, 1); PG8_STAGE(PG8_SB(0, 0), b2, voffB); PG8_STAGE(PG8_SB(0, 1), b2 + hstep, voffB); PG8_STAGE(PG8_SA(0, 0), a2, voffA);
;             PG8_WAIT_V(8); PG8_WAIT_L(0); PG8_BAR; PG8_MMA(1, 0, At, B0); PG8_MMA(1, 1, At, B1); PG8_BAR; PG8_SCHED;
.Lk126_body:
	ds_read_b128 v[128:131], v145
	ds_read_b128 v[132:135], v145 offset:1024
	ds_read_b128 v[164:167], v145 offset:2048
	ds_read_b128 v[168:171], v145 offset:3072
	v_add_u32_e32 v145, s58, v178
	ds_read_b128 v[172:175], v145
	ds_read_b128 v[180:183], v145 offset:1024
	ds_read_b128 v[184:187], v145 offset:2048
	ds_read_b128 v[188:191], v145 offset:3072
	v_lshl_add_u64 v[150:151], s[2:3], 0, v[160:161]
	s_add_i32 m0, s36, 0xc000
	ds_read_b128 v[192:195], v179
	ds_read_b128 v[196:199], v179 offset:1024
	ds_read_b128 v[200:203], v179 offset:2048
	ds_read_b128 v[222:225], v179 offset:3072
	ds_read_b128 v[226:229], v179 offset:4096
	ds_read_b128 v[230:233], v179 offset:5120
	ds_read_b128 v[234:237], v179 offset:6144
	ds_read_b128 v[238:241], v179 offset:7168
	global_load_lds_dwordx4 v[150:151], off
	v_lshl_add_u64 v[150:151], s[2:3], 0, v[162:163]
	s_add_i32 m0, s36, 0xe000
	s_nop 0
	global_load_lds_dwordx4 v[150:151], off
	s_waitcnt vmcnt(8)
	s_waitcnt lgkmcnt(0)
	s_barrier
	s_setprio 1
	s_waitcnt lgkmcnt(0)
	v_mfma_f32_16x16x32_bf16 v[124:127], v[128:131], v[192:195], v[124:127]
	v_mfma_f32_16x16x32_bf16 v[120:123], v[164:167], v[192:195], v[120:123]
	v_mfma_f32_16x16x32_bf16 v[108:111], v[128:131], v[200:203], v[108:111]
	v_mfma_f32_16x16x32_bf16 v[104:107], v[164:167], v[200:203], v[104:107]
	v_mfma_f32_16x16x32_bf16 v[92:95], v[128:131], v[226:229], v[92:95]
	v_mfma_f32_16x16x32_bf16 v[88:91], v[164:167], v[226:229], v[88:91]
	v_mfma_f32_16x16x32_bf16 v[76:79], v[128:131], v[234:237], v[76:79]
	v_mfma_f32_16x16x32_bf16 v[72:75], v[164:167], v[234:237], v[72:75]
	v_mfma_f32_16x16x32_bf16 v[124:127], v[132:135], v[196:199], v[124:127]
	v_mfma_f32_16x16x32_bf16 v[120:123], v[168:171], v[196:199], v[120:123]
	v_mfma_f32_16x16x32_bf16 v[108:111], v[132:135], v[222:225], v[108:111]
	v_mfma_f32_16x16x32_bf16 v[104:107], v[168:171], v[222:225], v[104:107]
	v_mfma_f32_16x16x32_bf16 v[92:95], v[132:135], v[230:233], v[92:95]
	v_mfma_f32_16x16x32_bf16 v[88:91], v[168:171], v[230:233], v[88:91]
	v_mfma_f32_16x16x32_bf16 v[76:79], v[132:135], v[238:241], v[76:79]
	v_mfma_f32_16x16x32_bf16 v[72:75], v[168:171], v[238:241], v[72:75]
	s_setprio 0
	s_setprio 1
	v_mfma_f32_16x16x32_bf16 v[116:119], v[172:175], v[192:195], v[116:119]
	v_mfma_f32_16x16x32_bf16 v[112:115], v[184:187], v[192:195], v[112:115]
	v_mfma_f32_16x16x32_bf16 v[100:103], v[172:175], v[200:203], v[100:103]
	v_mfma_f32_16x16x32_bf16 v[96:99], v[184:187], v[200:203], v[96:99]
	v_mfma_f32_16x16x32_bf16 v[84:87], v[172:175], v[226:229], v[84:87]
	v_mfma_f32_16x16x32_bf16 v[80:83], v[184:187], v[226:229], v[80:83]
	v_mfma_f32_16x16x32_bf16 v[68:71], v[172:175], v[234:237], v[68:71]
	v_mfma_f32_16x16x32_bf16 v[64:67], v[184:187], v[234:237], v[64:67]
	v_mfma_f32_16x16x32_bf16 v[116:119], v[180:183], v[196:199], v[116:119]
	v_mfma_f32_16x16x32_bf16 v[112:115], v[188:191], v[196:199], v[112:115]
	v_mfma_f32_16x16x32_bf16 v[100:103], v[180:183], v[222:225], v[100:103]
	v_mfma_f32_16x16x32_bf16 v[96:99], v[188:191], v[222:225], v[96:99]
	v_mfma_f32_16x16x32_bf16 v[84:87], v[180:183], v[230:233], v[84:87]
	v_mfma_f32_16x16x32_bf16 v[80:83], v[188:191], v[230:233], v[80:83]
	v_mfma_f32_16x16x32_bf16 v[68:71], v[180:183], v[238:241], v[68:71]
	v_mfma_f32_16x16x32_bf16 v[64:67], v[188:191], v[238:241], v[64:67]
	s_setprio 0
	s_barrier
	s_add_i32 s55, s55, s35
	v_lshl_add_u64 v[150:151], s[26:27], 0, v[138:139]
	s_mov_b32 m0, s55
	ds_read_b128 v[192:195], v179 offset:16384
	ds_read_b128 v[196:199], v179 offset:17408
	ds_read_b128 v[200:203], v179 offset:18432
	ds_read_b128 v[222:225], v179 offset:19456
	ds_read_b128 v[226:229], v179 offset:20480
	ds_read_b128 v[230:233], v179 offset:21504
	ds_read_b128 v[234:237], v179 offset:22528
	ds_read_b128 v[238:241], v179 offset:23552
	global_load_lds_dwordx4 v[150:151], off
	s_add_i32 m0, s55, 0x2000
	s_add_u32 s56, s26, 0x40000
	v_lshl_add_u64 v[176:177], s[26:27], 0, v[142:143]
	s_addc_u32 s57, s27, 0
	s_add_i32 s55, s58, s35
	global_load_lds_dwordx4 v[176:177], off
	v_lshl_add_u64 v[204:205], s[56:57], 0, v[138:139]
	s_mov_b32 m0, s55
	v_lshl_add_u64 v[206:207], s[28:29], 0, v[140:141]
	global_load_lds_dwordx4 v[204:205], off
	v_lshl_add_u64 v[204:205], s[56:57], 0, v[142:143]
	s_add_i32 m0, s55, 0x2000
	s_nop 0
	global_load_lds_dwordx4 v[204:205], off
	v_lshl_add_u64 v[204:205], s[28:29], 0, v[136:137]
	s_mov_b32 m0, s36
	s_nop 0
	global_load_lds_dwordx4 v[204:205], off
	s_mov_b32 m0, s37
	s_nop 0
	global_load_lds_dwordx4 v[206:207], off
	s_waitcnt vmcnt(8)
	s_waitcnt lgkmcnt(0)
	s_barrier
; #define PG8_STAGE(bufoff, gbase, voff) do { _Pragma("unroll") for (int _i = 0; _i < 2; ++_i) \
;         __builtin_amdgcn_global_load_lds((const unsigned*)((const char*)(gbase) + (voff)[_i]), (PG8_LAS unsigned*)(lds + (bufoff) + ldsw + _i * 8192), 16, 0, 0); } while (0)
; #define PG8_LDA(dst, b, h) do { _Pragma("unroll") for (int m = 0; m < 4; ++m) _Pragma("unroll") for (int k = 0; k < 2; ++k) dst[m][k] = *(const PG8_LAS bf16x8*)(lds + PG8_SA(b, h) + aoff + m * 2048 + k * 1024); } while (0)
; #define PG8_LDB(dst, b, h) do { _Pragma("unroll") for (int n = 0; n < 2; ++n) _Pragma("unroll") for (int k = 0; k < 2; ++k) dst[n][k] = *(const PG8_LAS bf16x8*)(lds + PG8_SB(b, h) + boff + n * 2048 + k * 1024); } while (0)
; #define PG8_MMA(ai, bj, At, Bt) do { __builtin_amdgcn_s_setprio(1); _Pragma("unroll") for (int m = 0; m < 4; ++m) _Pragma("unroll") for (int n = 0; n < 2; ++n) _Pragma("unroll") for (int k = 0; k < 2; ++k) \
;         acc[ai][bj][m][n] = __builtin_amdgcn_mfma_f32_16x16x32_bf16(Bt[n][k], At[m][k], acc[ai][bj][m][n], 0, 0, 0); __builtin_amdgcn_s_setprio(0); } while (0)
; #define PG8_WAIT_V(n) asm volatile("s_waitcnt vmcnt(" #n ")" ::: "memory")
; #define PG8_WAIT_L(n) asm volatile("s_waitcnt lgkmcnt(" #n ")" ::: "memory")
; #define PG8_BAR __builtin_amdgcn_s_barrier()
; #define PG8_SCHED __builtin_amdgcn_sched_barrier(0)
; template <class Epi, class Sched, bool ALIGN_EPI = false, bool SP2 = false>
; __device__ __forceinline__ void gemm_phase(PG8_LAS unsigned char* lds, const Gemm g, const Sched& S, const Epi& E, const int tid) {
;     ...
;             PG8_WAIT_V(8); PG8_WAIT_L(0); PG8_BAR; PG8_MMA(1, 0, At, B0); PG8_MMA(1, 1, At, B1); PG8_BAR; PG8_SCHED;
;             PG8_LDB(B0, 1, 0); PG8_LDB(B1, 1, 1); PG8_SCHED; PG8_LDA(At, 1, 0); PG8_STAGE(PG8_SA(0, 1), a2 + hstep, voffA);
;             PG8_WAIT_V(8); PG8_WAIT_L(0); PG8_BAR; PG8_MMA(0, 0, At, B0); PG8_MMA(0, 1, At, B1); PG8_BAR; PG8_SCHED;
	s_setprio 1
	s_waitcnt lgkmcnt(0)
	v_mfma_f32_16x16x32_bf16 v[60:63], v[128:131], v[192:195], v[60:63]
	v_mfma_f32_16x16x32_bf16 v[56:59], v[164:167], v[192:195], v[56:59]
	v_mfma_f32_16x16x32_bf16 v[44:47], v[128:131], v[200:203], v[44:47]
	v_mfma_f32_16x16x32_bf16 v[40:43], v[164:167], v[200:203], v[40:43]
	v_mfma_f32_16x16x32_bf16 v[28:31], v[128:131], v[226:229], v[28:31]
	v_mfma_f32_16x16x32_bf16 v[24:27], v[164:167], v[226:229], v[24:27]
	v_mfma_f32_16x16x32_bf16 v[12:15], v[128:131], v[234:237], v[12:15]
	v_mfma_f32_16x16x32_bf16 v[8:11], v[164:167], v[234:237], v[8:11]
	v_mfma_f32_16x16x32_bf16 v[60:63], v[132:135], v[196:199], v[60:63]
	v_mfma_f32_16x16x32_bf16 v[56:59], v[168:171], v[196:199], v[56:59]
	v_mfma_f32_16x16x32_bf16 v[44:47], v[132:135], v[222:225], v[44:47]
	v_mfma_f32_16x16x32_bf16 v[40:43], v[168:171], v[222:225], v[40:43]
	v_mfma_f32_16x16x32_bf16 v[28:31], v[132:135], v[230:233], v[28:31]
	v_mfma_f32_16x16x32_bf16 v[24:27], v[168:171], v[230:233], v[24:27]
	v_mfma_f32_16x16x32_bf16 v[12:15], v[132:135], v[238:241], v[12:15]
	v_mfma_f32_16x16x32_bf16 v[8:11], v[168:171], v[238:241], v[8:11]
	s_setprio 0
	s_setprio 1
	v_mfma_f32_16x16x32_bf16 v[52:55], v[172:175], v[192:195], v[52:55]
	v_mfma_f32_16x16x32_bf16 v[48:51], v[184:187], v[192:195], v[48:51]
	v_mfma_f32_16x16x32_bf16 v[36:39], v[172:175], v[200:203], v[36:39]
	v_mfma_f32_16x16x32_bf16 v[32:35], v[184:187], v[200:203], v[32:35]
	v_mfma_f32_16x16x32_bf16 v[20:23], v[172:175], v[226:229], v[20:23]
	v_mfma_f32_16x16x32_bf16 v[16:19], v[184:187], v[226:229], v[16:19]
	v_mfma_f32_16x16x32_bf16 v[4:7], v[172:175], v[234:237], v[4:7]
	v_mfma_f32_16x16x32_bf16 v[0:3], v[184:187], v[234:237], v[0:3]
	v_mfma_f32_16x16x32_bf16 v[52:55], v[180:183], v[196:199], v[52:55]
	v_mfma_f32_16x16x32_bf16 v[48:51], v[188:191], v[196:199], v[48:51]
	v_mfma_f32_16x16x32_bf16 v[36:39], v[180:183], v[222:225], v[36:39]
	v_mfma_f32_16x16x32_bf16 v[32:35], v[188:191], v[222:225], v[32:35]
	v_mfma_f32_16x16x32_bf16 v[20:23], v[180:183], v[230:233], v[20:23]
	v_mfma_f32_16x16x32_bf16 v[16:19], v[188:191], v[230:233], v[16:19]
	v_mfma_f32_16x16x32_bf16 v[4:7], v[180:183], v[238:241], v[4:7]
	v_mfma_f32_16x16x32_bf16 v[0:3], v[188:191], v[238:241], v[0:3]
	s_setprio 0
	s_barrier
	s_add_i32 s55, 0, 0x18000
	v_add_u32_e32 v145, s55, v178
	s_add_i32 s56, 0, 0x1c000
	ds_read_b128 v[128:131], v145
	ds_read_b128 v[132:135], v145 offset:1024
	ds_read_b128 v[164:167], v145 offset:2048
	ds_read_b128 v[168:171], v145 offset:3072
	v_add_u32_e32 v145, s56, v178
	ds_read_b128 v[172:175], v145
	ds_read_b128 v[180:183], v145 offset:1024
	ds_read_b128 v[184:187], v145 offset:2048
	ds_read_b128 v[188:191], v145 offset:3072
	s_add_u32 s28, s28, 0x40000
	s_addc_u32 s29, s29, 0
	s_mov_b32 m0, s38
	v_lshl_add_u64 v[242:243], s[28:29], 0, v[136:137]
	ds_read_b128 v[192:195], v179 offset:32768
	ds_read_b128 v[196:199], v179 offset:33792
	ds_read_b128 v[200:203], v179 offset:34816
	ds_read_b128 v[222:225], v179 offset:35840
	ds_read_b128 v[226:229], v179 offset:36864
	ds_read_b128 v[230:233], v179 offset:37888
	ds_read_b128 v[234:237], v179 offset:38912
	ds_read_b128 v[238:241], v179 offset:39936
	global_load_lds_dwordx4 v[242:243], off
	v_lshl_add_u64 v[242:243], s[28:29], 0, v[140:141]
	s_mov_b32 m0, s39
	s_nop 0
	global_load_lds_dwordx4 v[242:243], off
	s_waitcnt vmcnt(8)
	s_waitcnt lgkmcnt(0)
	s_barrier
	s_setprio 1
	s_waitcnt lgkmcnt(0)
	v_mfma_f32_16x16x32_bf16 v[124:127], v[128:131], v[192:195], v[124:127]
	v_mfma_f32_16x16x32_bf16 v[120:123], v[164:167], v[192:195], v[120:123]
	v_mfma_f32_16x16x32_bf16 v[108:111], v[128:131], v[200:203], v[108:111]
	v_mfma_f32_16x16x32_bf16 v[104:107], v[164:167], v[200:203], v[104:107]
	v_mfma_f32_16x16x32_bf16 v[92:95], v[128:131], v[226:229], v[92:95]
	v_mfma_f32_16x16x32_bf16 v[88:91], v[164:167], v[226:229], v[88:91]
	v_mfma_f32_16x16x32_bf16 v[76:79], v[128:131], v[234:237], v[76:79]
	v_mfma_f32_16x16x32_bf16 v[72:75], v[164:167], v[234:237], v[72:75]
	v_mfma_f32_16x16x32_bf16 v[124:127], v[132:135], v[196:199], v[124:127]
	v_mfma_f32_16x16x32_bf16 v[120:123], v[168:171], v[196:199], v[120:123]
	v_mfma_f32_16x16x32_bf16 v[108:111], v[132:135], v[222:225], v[108:111]
	v_mfma_f32_16x16x32_bf16 v[104:107], v[168:171], v[222:225], v[104:107]
	v_mfma_f32_16x16x32_bf16 v[92:95], v[132:135], v[230:233], v[92:95]
	v_mfma_f32_16x16x32_bf16 v[88:91], v[168:171], v[230:233], v[88:91]
	v_mfma_f32_16x16x32_bf16 v[76:79], v[132:135], v[238:241], v[76:79]
	v_mfma_f32_16x16x32_bf16 v[72:75], v[168:171], v[238:241], v[72:75]
	s_setprio 0
	s_setprio 1
	v_mfma_f32_16x16x32_bf16 v[116:119], v[172:175], v[192:195], v[116:119]
	v_mfma_f32_16x16x32_bf16 v[112:115], v[184:187], v[192:195], v[112:115]
	v_mfma_f32_16x16x32_bf16 v[100:103], v[172:175], v[200:203], v[100:103]
	v_mfma_f32_16x16x32_bf16 v[96:99], v[184:187], v[200:203], v[96:99]
	v_mfma_f32_16x16x32_bf16 v[84:87], v[172:175], v[226:229], v[84:87]
	v_mfma_f32_16x16x32_bf16 v[80:83], v[184:187], v[226:229], v[80:83]
	v_mfma_f32_16x16x32_bf16 v[68:71], v[172:175], v[234:237], v[68:71]
	v_mfma_f32_16x16x32_bf16 v[64:67], v[184:187], v[234:237], v[64:67]
	v_mfma_f32_16x16x32_bf16 v[116:119], v[180:183], v[196:199], v[116:119]
	v_mfma_f32_16x16x32_bf16 v[112:115], v[188:191], v[196:199], v[112:115]
	v_mfma_f32_16x16x32_bf16 v[100:103], v[180:183], v[222:225], v[100:103]
	v_mfma_f32_16x16x32_bf16 v[96:99], v[188:191], v[222:225], v[96:99]
	v_mfma_f32_16x16x32_bf16 v[84:87], v[180:183], v[230:233], v[84:87]
	v_mfma_f32_16x16x32_bf16 v[80:83], v[188:191], v[230:233], v[80:83]
	v_mfma_f32_16x16x32_bf16 v[68:71], v[180:183], v[238:241], v[68:71]
	v_mfma_f32_16x16x32_bf16 v[64:67], v[188:191], v[238:241], v[64:67]
	s_setprio 0
	s_barrier
; #define PG8_STAGE(bufoff, gbase, voff) do { _Pragma("unroll") for (int _i = 0; _i < 2; ++_i) \
;         __builtin_amdgcn_global_load_lds((const unsigned*)((const char*)(gbase) + (voff)[_i]), (PG8_LAS unsigned*)(lds + (bufoff) + ldsw + _i * 8192), 16, 0, 0); } while (0)
; #define PG8_LDA(dst, b, h) do { _Pragma("unroll") for (int m = 0; m < 4; ++m) _Pragma("unroll") for (int k = 0; k < 2; ++k) dst[m][k] = *(const PG8_LAS bf16x8*)(lds + PG8_SA(b, h) + aoff + m * 2048 + k * 1024); } while (0)
; #define PG8_MMA(ai, bj, At, Bt) do { __builtin_amdgcn_s_setprio(1); _Pragma("unroll") for (int m = 0; m < 4; ++m) _Pragma("unroll") for (int n = 0; n < 2; ++n) _Pragma("unroll") for (int k = 0; k < 2; ++k) \
;         acc[ai][bj][m][n] = __builtin_amdgcn_mfma_f32_16x16x32_bf16(Bt[n][k], At[m][k], acc[ai][bj][m][n], 0, 0, 0); __builtin_amdgcn_s_setprio(0); } while (0)
; #define PG8_WAIT_V(n) asm volatile("s_waitcnt vmcnt(" #n ")" ::: "memory")
; #define PG8_WAIT_L(n) asm volatile("s_waitcnt lgkmcnt(" #n ")" ::: "memory")
; #define PG8_BAR __builtin_amdgcn_s_barrier()
; #define PG8_SCHED __builtin_amdgcn_sched_barrier(0)
; template <class Epi, class Sched, bool ALIGN_EPI = false, bool SP2 = false>
; __device__ __forceinline__ void gemm_phase(PG8_LAS unsigned char* lds, const Gemm g, const Sched& S, const Epi& E, const int tid) {
;     ...
;         for (int t = 0; t < nt; t += 2) {
;             const bool last = (t == nt - 2);
;             const char* a1 = cA + (size_t)(t + 1) * kstep;
;             const char* a2 = last ? nA : cA + (size_t)(t + 2) * kstep; const char* b2 = last ? nB : cB + (size_t)(t + 2) * kstep;
;             const char* a3 = a2 + kstep; const char* b3 = b2 + kstep;
;     ...
;             PG8_LDA(At, 1, 1); PG8_STAGE(PG8_SB(1, 0), b3, voffB); PG8_STAGE(PG8_SB(1, 1), b3 + hstep, voffB); PG8_STAGE(PG8_SA(1, 0), a3, voffA);
;             PG8_WAIT_V(8); PG8_WAIT_L(0); PG8_BAR; PG8_MMA(1, 0, At, B0); PG8_MMA(1, 1, At, B1); PG8_BAR; PG8_SCHED;
	s_add_i32 s28, s55, s35
	v_lshl_add_u64 v[150:151], v[150:151], 0, s[60:61]
	s_mov_b32 m0, s28
	ds_read_b128 v[192:195], v179 offset:49152
	ds_read_b128 v[196:199], v179 offset:50176
	ds_read_b128 v[200:203], v179 offset:51200
	ds_read_b128 v[222:225], v179 offset:52224
	ds_read_b128 v[226:229], v179 offset:53248
	ds_read_b128 v[230:233], v179 offset:54272
	ds_read_b128 v[234:237], v179 offset:55296
	ds_read_b128 v[238:241], v179 offset:56320
	global_load_lds_dwordx4 v[150:151], off
	s_add_i32 m0, s28, 0x2000
	s_add_u32 s26, s26, 0x40080
	v_lshl_add_u64 v[150:151], v[176:177], 0, s[60:61]
	s_addc_u32 s27, s27, 0
	s_add_i32 s28, s56, s35
	global_load_lds_dwordx4 v[150:151], off
	v_lshl_add_u64 v[150:151], s[26:27], 0, v[138:139]
	s_mov_b32 m0, s28
	s_nop 0
	global_load_lds_dwordx4 v[150:151], off
	v_lshl_add_u64 v[150:151], s[26:27], 0, v[142:143]
	s_add_i32 m0, s28, 0x2000
	s_nop 0
	global_load_lds_dwordx4 v[150:151], off
	v_lshl_add_u64 v[150:151], v[204:205], 0, s[60:61]
	s_mov_b32 m0, s45
	s_nop 0
	global_load_lds_dwordx4 v[150:151], off
	v_lshl_add_u64 v[150:151], v[206:207], 0, s[60:61]
	s_mov_b32 m0, s46
	s_nop 0
	global_load_lds_dwordx4 v[150:151], off
	s_waitcnt vmcnt(8)
	s_waitcnt lgkmcnt(0)
	s_barrier
	s_setprio 1
	s_waitcnt lgkmcnt(0)
	v_mfma_f32_16x16x32_bf16 v[60:63], v[128:131], v[192:195], v[60:63]
	v_mfma_f32_16x16x32_bf16 v[56:59], v[164:167], v[192:195], v[56:59]
	v_mfma_f32_16x16x32_bf16 v[44:47], v[128:131], v[200:203], v[44:47]
	v_mfma_f32_16x16x32_bf16 v[40:43], v[164:167], v[200:203], v[40:43]
	v_mfma_f32_16x16x32_bf16 v[28:31], v[128:131], v[226:229], v[28:31]
	v_mfma_f32_16x16x32_bf16 v[24:27], v[164:167], v[226:229], v[24:27]
	v_mfma_f32_16x16x32_bf16 v[12:15], v[128:131], v[234:237], v[12:15]
	v_mfma_f32_16x16x32_bf16 v[8:11], v[164:167], v[234:237], v[8:11]
	v_mfma_f32_16x16x32_bf16 v[60:63], v[132:135], v[196:199], v[60:63]
	v_mfma_f32_16x16x32_bf16 v[56:59], v[168:171], v[196:199], v[56:59]
	v_mfma_f32_16x16x32_bf16 v[44:47], v[132:135], v[222:225], v[44:47]
	v_mfma_f32_16x16x32_bf16 v[40:43], v[168:171], v[222:225], v[40:43]
	v_mfma_f32_16x16x32_bf16 v[28:31], v[132:135], v[230:233], v[28:31]
	v_mfma_f32_16x16x32_bf16 v[24:27], v[168:171], v[230:233], v[24:27]
	v_mfma_f32_16x16x32_bf16 v[12:15], v[132:135], v[238:241], v[12:15]
	v_mfma_f32_16x16x32_bf16 v[8:11], v[168:171], v[238:241], v[8:11]
	s_setprio 0
	s_setprio 1
	v_mfma_f32_16x16x32_bf16 v[52:55], v[172:175], v[192:195], v[52:55]
	v_mfma_f32_16x16x32_bf16 v[48:51], v[184:187], v[192:195], v[48:51]
	v_mfma_f32_16x16x32_bf16 v[36:39], v[172:175], v[200:203], v[36:39]
	v_mfma_f32_16x16x32_bf16 v[32:35], v[184:187], v[200:203], v[32:35]
	v_mfma_f32_16x16x32_bf16 v[20:23], v[172:175], v[226:229], v[20:23]
	v_mfma_f32_16x16x32_bf16 v[16:19], v[184:187], v[226:229], v[16:19]
	v_mfma_f32_16x16x32_bf16 v[4:7], v[172:175], v[234:237], v[4:7]
	v_mfma_f32_16x16x32_bf16 v[0:3], v[184:187], v[234:237], v[0:3]
	v_mfma_f32_16x16x32_bf16 v[52:55], v[180:183], v[196:199], v[52:55]
	v_mfma_f32_16x16x32_bf16 v[48:51], v[188:191], v[196:199], v[48:51]
	v_mfma_f32_16x16x32_bf16 v[36:39], v[180:183], v[222:225], v[36:39]
	v_mfma_f32_16x16x32_bf16 v[32:35], v[188:191], v[222:225], v[32:35]
	v_mfma_f32_16x16x32_bf16 v[20:23], v[180:183], v[230:233], v[20:23]
	v_mfma_f32_16x16x32_bf16 v[16:19], v[188:191], v[230:233], v[16:19]
	v_mfma_f32_16x16x32_bf16 v[4:7], v[180:183], v[238:241], v[4:7]
	v_mfma_f32_16x16x32_bf16 v[0:3], v[188:191], v[238:241], v[0:3]
	s_setprio 0
	s_add_i32 s54, s54, 2
	s_add_u32 s2, s2, 0x100
	s_addc_u32 s3, s3, 0
	s_add_u32 s52, s52, 0x100
	s_addc_u32 s53, s53, 0
	s_add_u32 s26, s2, 0xfffc0080
	s_addc_u32 s27, s3, -1
	s_add_i32 s55, 0, 0x10000
	s_cmp_eq_u32 s54, 12
	s_cselect_b32 s29, s1, s27
	s_cselect_b32 s28, s21, s26
	v_add_u32_e32 v145, s55, v178
	s_cselect_b32 s27, s19, s53
	s_cselect_b32 s26, s51, s52
	s_add_i32 s58, 0, 0x14000
	s_cmp_gt_u32 s54, 13
	s_barrier
	s_cbranch_scc0 .Lk126_body
	s_and_b64 vcc, exec, s[16:17]
	s_cbranch_vccz .LBB0_129
	s_barrier

; #define PG8_STAGE(bufoff, gbase, voff) do { _Pragma("unroll") for (int _i = 0; _i < 2; ++_i) \
;         __builtin_amdgcn_global_load_lds((const unsigned*)((const char*)(gbase) + (voff)[_i]), (PG8_LAS unsigned*)(lds + (bufoff) + ldsw + _i * 8192), 16, 0, 0); } while (0)
; #define PG8_LDA(dst, b, h) do { _Pragma("unroll") for (int m = 0; m < 4; ++m) _Pragma("unroll") for (int k = 0; k < 2; ++k) dst[m][k] = *(const PG8_LAS bf16x8*)(lds + PG8_SA(b, h) + aoff + m * 2048 + k * 1024); } while (0)
; #define PG8_LDB(dst, b, h) do { _Pragma("unroll") for (int n = 0; n < 2; ++n) _Pragma("unroll") for (int k = 0; k < 2; ++k) dst[n][k] = *(const PG8_LAS bf16x8*)(lds + PG8_SB(b, h) + boff + n * 2048 + k * 1024); } while (0)
; #define PG8_MMA(ai, bj, At, Bt) do { __builtin_amdgcn_s_setprio(1); _Pragma("unroll") for (int m = 0; m < 4; ++m) _Pragma("unroll") for (int n = 0; n < 2; ++n) _Pragma("unroll") for (int k = 0; k < 2; ++k) \
;         acc[ai][bj][m][n] = __builtin_amdgcn_mfma_f32_16x16x32_bf16(Bt[n][k], At[m][k], acc[ai][bj][m][n], 0, 0, 0); __builtin_amdgcn_s_setprio(0); } while (0)
; #define PG8_WAIT_V(n) asm volatile("s_waitcnt vmcnt(" #n ")" ::: "memory")
; #define PG8_WAIT_L(n) asm volatile("s_waitcnt lgkmcnt(" #n ")" ::: "memory")
; #define PG8_BAR __builtin_amdgcn_s_barrier()
; #define PG8_SCHED __builtin_amdgcn_sched_barrier(0)
; template <class Epi, class Sched, bool ALIGN_EPI = false, bool SP2 = false>
; __device__ __forceinline__ void gemm_phase(PG8_LAS unsigned char* lds, const Gemm g, const Sched& S, const Epi& E, const int tid) {
;     ...
;             if constexpr (SP2) {
;             PG8_LDB(B0, 0, 0); PG8_LDB(B1, 0, 1); PG8_SCHED; PG8_LDA(At, 0, 0); PG8_STAGE(PG8_SA(1, 1), a1 + hstep, voffA);
;             PG8_WAIT_V(8); PG8_WAIT_L(0); PG8_BAR; PG8_MMA(0, 0, At, B0); PG8_MMA(0, 1, At, B1); PG8_BAR; PG8_SCHED;
;             PG8_LDA(At, 0, 1); PG8_STAGE(PG8_SB(0, 0), b2, voffB); PG8_STAGE(PG8_SB(0, 1), b2 + hstep, voffB); PG8_STAGE(PG8_SA(0, 0), a2, voffA);
;             PG8_WAIT_V(8); PG8_WAIT_L(0); PG8_BAR; PG8_MMA(1, 0, At, B0); PG8_MMA(1, 1, At, B1); PG8_BAR; PG8_SCHED;
.Lk881_body:
	ds_read_b128 v[154:157], v138
	ds_read_b128 v[158:161], v138 offset:1024
	ds_read_b128 v[162:165], v138 offset:2048
	ds_read_b128 v[166:169], v138 offset:3072
	v_add_u32_e32 v138, s63, v224
	ds_read_b128 v[170:173], v138
	ds_read_b128 v[174:177], v138 offset:1024
	ds_read_b128 v[178:181], v138 offset:2048
	ds_read_b128 v[182:185], v138 offset:3072
	v_lshl_add_u64 v[138:139], s[30:31], 0, v[134:135]
	s_add_i32 m0, s42, 0xc000
	ds_read_b128 v[186:189], v226
	ds_read_b128 v[190:193], v226 offset:1024
	ds_read_b128 v[194:197], v226 offset:2048
	ds_read_b128 v[198:201], v226 offset:3072
	ds_read_b128 v[202:205], v226 offset:4096
	ds_read_b128 v[228:231], v226 offset:5120
	ds_read_b128 v[232:235], v226 offset:6144
	ds_read_b128 v[236:239], v226 offset:7168
	global_load_lds_dwordx4 v[138:139], off
	v_lshl_add_u64 v[138:139], s[30:31], 0, v[136:137]
	s_add_i32 m0, s42, 0xe000
	s_nop 0
	global_load_lds_dwordx4 v[138:139], off
	s_waitcnt vmcnt(8)
	s_waitcnt lgkmcnt(0)
	s_barrier
	s_setprio 1
	s_waitcnt lgkmcnt(0)
	v_mfma_f32_16x16x32_bf16 v[124:127], v[154:157], v[186:189], v[124:127]
	v_mfma_f32_16x16x32_bf16 v[120:123], v[162:165], v[186:189], v[120:123]
	v_mfma_f32_16x16x32_bf16 v[116:119], v[154:157], v[194:197], v[116:119]
	v_mfma_f32_16x16x32_bf16 v[112:115], v[162:165], v[194:197], v[112:115]
	v_mfma_f32_16x16x32_bf16 v[108:111], v[154:157], v[202:205], v[108:111]
	v_mfma_f32_16x16x32_bf16 v[104:107], v[162:165], v[202:205], v[104:107]
	v_mfma_f32_16x16x32_bf16 v[100:103], v[154:157], v[232:235], v[100:103]
	v_mfma_f32_16x16x32_bf16 v[96:99], v[162:165], v[232:235], v[96:99]
	v_mfma_f32_16x16x32_bf16 v[124:127], v[158:161], v[190:193], v[124:127]
	v_mfma_f32_16x16x32_bf16 v[120:123], v[166:169], v[190:193], v[120:123]
	v_mfma_f32_16x16x32_bf16 v[116:119], v[158:161], v[198:201], v[116:119]
	v_mfma_f32_16x16x32_bf16 v[112:115], v[166:169], v[198:201], v[112:115]
	v_mfma_f32_16x16x32_bf16 v[108:111], v[158:161], v[228:231], v[108:111]
	v_mfma_f32_16x16x32_bf16 v[104:107], v[166:169], v[228:231], v[104:107]
	v_mfma_f32_16x16x32_bf16 v[100:103], v[158:161], v[236:239], v[100:103]
	v_mfma_f32_16x16x32_bf16 v[96:99], v[166:169], v[236:239], v[96:99]
	s_setprio 0
	s_setprio 1
	v_mfma_f32_16x16x32_bf16 v[60:63], v[170:173], v[186:189], v[60:63]
	v_mfma_f32_16x16x32_bf16 v[56:59], v[178:181], v[186:189], v[56:59]
	v_mfma_f32_16x16x32_bf16 v[52:55], v[170:173], v[194:197], v[52:55]
	v_mfma_f32_16x16x32_bf16 v[48:51], v[178:181], v[194:197], v[48:51]
	v_mfma_f32_16x16x32_bf16 v[44:47], v[170:173], v[202:205], v[44:47]
	v_mfma_f32_16x16x32_bf16 v[40:43], v[178:181], v[202:205], v[40:43]
	v_mfma_f32_16x16x32_bf16 v[36:39], v[170:173], v[232:235], v[36:39]
	v_mfma_f32_16x16x32_bf16 v[32:35], v[178:181], v[232:235], v[32:35]
	v_mfma_f32_16x16x32_bf16 v[60:63], v[174:177], v[190:193], v[60:63]
	v_mfma_f32_16x16x32_bf16 v[56:59], v[182:185], v[190:193], v[56:59]
	v_mfma_f32_16x16x32_bf16 v[52:55], v[174:177], v[198:201], v[52:55]
	v_mfma_f32_16x16x32_bf16 v[48:51], v[182:185], v[198:201], v[48:51]
	v_mfma_f32_16x16x32_bf16 v[44:47], v[174:177], v[228:231], v[44:47]
	v_mfma_f32_16x16x32_bf16 v[40:43], v[182:185], v[228:231], v[40:43]
	v_mfma_f32_16x16x32_bf16 v[36:39], v[174:177], v[236:239], v[36:39]
	v_mfma_f32_16x16x32_bf16 v[32:35], v[182:185], v[236:239], v[32:35]
	s_setprio 0
	s_barrier
	s_add_i32 s62, s62, s41
	v_lshl_add_u64 v[138:139], s[60:61], 0, v[146:147]
	s_mov_b32 m0, s62
	ds_read_b128 v[186:189], v226 offset:16384
	ds_read_b128 v[190:193], v226 offset:17408
	ds_read_b128 v[194:197], v226 offset:18432
	ds_read_b128 v[198:201], v226 offset:19456
	ds_read_b128 v[202:205], v226 offset:20480
	ds_read_b128 v[228:231], v226 offset:21504
	ds_read_b128 v[232:235], v226 offset:22528
	ds_read_b128 v[236:239], v226 offset:23552
	global_load_lds_dwordx4 v[138:139], off
	s_add_i32 m0, s62, 0x2000
	v_lshl_add_u64 v[142:143], s[60:61], 0, v[132:133]
	s_add_u32 s60, s60, s10
	s_addc_u32 s61, s61, 0
	s_add_i32 s62, s63, s41
	global_load_lds_dwordx4 v[142:143], off
	v_lshl_add_u64 v[240:241], s[60:61], 0, v[146:147]
	s_mov_b32 m0, s62
	v_lshl_add_u64 v[242:243], s[60:61], 0, v[132:133]
	global_load_lds_dwordx4 v[240:241], off
	s_add_i32 m0, s62, 0x2000
	v_lshl_add_u64 v[244:245], s[34:35], 0, v[128:129]
	global_load_lds_dwordx4 v[242:243], off
	s_mov_b32 m0, s42
	v_lshl_add_u64 v[246:247], s[34:35], 0, v[130:131]
	global_load_lds_dwordx4 v[244:245], off
	s_mov_b32 m0, s43
	s_nop 0
	global_load_lds_dwordx4 v[246:247], off
	s_waitcnt vmcnt(8)
	s_waitcnt lgkmcnt(0)
	s_barrier
; #define PG8_STAGE(bufoff, gbase, voff) do { _Pragma("unroll") for (int _i = 0; _i < 2; ++_i) \
;         __builtin_amdgcn_global_load_lds((const unsigned*)((const char*)(gbase) + (voff)[_i]), (PG8_LAS unsigned*)(lds + (bufoff) + ldsw + _i * 8192), 16, 0, 0); } while (0)
; #define PG8_LDA(dst, b, h) do { _Pragma("unroll") for (int m = 0; m < 4; ++m) _Pragma("unroll") for (int k = 0; k < 2; ++k) dst[m][k] = *(const PG8_LAS bf16x8*)(lds + PG8_SA(b, h) + aoff + m * 2048 + k * 1024); } while (0)
; #define PG8_LDB(dst, b, h) do { _Pragma("unroll") for (int n = 0; n < 2; ++n) _Pragma("unroll") for (int k = 0; k < 2; ++k) dst[n][k] = *(const PG8_LAS bf16x8*)(lds + PG8_SB(b, h) + boff + n * 2048 + k * 1024); } while (0)
; #define PG8_MMA(ai, bj, At, Bt) do { __builtin_amdgcn_s_setprio(1); _Pragma("unroll") for (int m = 0; m < 4; ++m) _Pragma("unroll") for (int n = 0; n < 2; ++n) _Pragma("unroll") for (int k = 0; k < 2; ++k) \
;         acc[ai][bj][m][n] = __builtin_amdgcn_mfma_f32_16x16x32_bf16(Bt[n][k], At[m][k], acc[ai][bj][m][n], 0, 0, 0); __builtin_amdgcn_s_setprio(0); } while (0)
; #define PG8_WAIT_V(n) asm volatile("s_waitcnt vmcnt(" #n ")" ::: "memory")
; #define PG8_WAIT_L(n) asm volatile("s_waitcnt lgkmcnt(" #n ")" ::: "memory")
; #define PG8_BAR __builtin_amdgcn_s_barrier()
; #define PG8_SCHED __builtin_amdgcn_sched_barrier(0)
; template <class Epi, class Sched, bool ALIGN_EPI = false, bool SP2 = false>
; __device__ __forceinline__ void gemm_phase(PG8_LAS unsigned char* lds, const Gemm g, const Sched& S, const Epi& E, const int tid) {
;     ...
;             PG8_WAIT_V(8); PG8_WAIT_L(0); PG8_BAR; PG8_MMA(1, 0, At, B0); PG8_MMA(1, 1, At, B1); PG8_BAR; PG8_SCHED;
;             PG8_LDB(B0, 1, 0); PG8_LDB(B1, 1, 1); PG8_SCHED; PG8_LDA(At, 1, 0); PG8_STAGE(PG8_SA(0, 1), a2 + hstep, voffA);
;             PG8_WAIT_V(8); PG8_WAIT_L(0); PG8_BAR; PG8_MMA(0, 0, At, B0); PG8_MMA(0, 1, At, B1); PG8_BAR; PG8_SCHED;
	s_setprio 1
	s_waitcnt lgkmcnt(0)
	v_mfma_f32_16x16x32_bf16 v[92:95], v[154:157], v[186:189], v[92:95]
	v_mfma_f32_16x16x32_bf16 v[88:91], v[162:165], v[186:189], v[88:91]
	v_mfma_f32_16x16x32_bf16 v[84:87], v[154:157], v[194:197], v[84:87]
	v_mfma_f32_16x16x32_bf16 v[80:83], v[162:165], v[194:197], v[80:83]
	v_mfma_f32_16x16x32_bf16 v[76:79], v[154:157], v[202:205], v[76:79]
	v_mfma_f32_16x16x32_bf16 v[72:75], v[162:165], v[202:205], v[72:75]
	v_mfma_f32_16x16x32_bf16 v[68:71], v[154:157], v[232:235], v[68:71]
	v_mfma_f32_16x16x32_bf16 v[64:67], v[162:165], v[232:235], v[64:67]
	v_mfma_f32_16x16x32_bf16 v[92:95], v[158:161], v[190:193], v[92:95]
	v_mfma_f32_16x16x32_bf16 v[88:91], v[166:169], v[190:193], v[88:91]
	v_mfma_f32_16x16x32_bf16 v[84:87], v[158:161], v[198:201], v[84:87]
	v_mfma_f32_16x16x32_bf16 v[80:83], v[166:169], v[198:201], v[80:83]
	v_mfma_f32_16x16x32_bf16 v[76:79], v[158:161], v[228:231], v[76:79]
	v_mfma_f32_16x16x32_bf16 v[72:75], v[166:169], v[228:231], v[72:75]
	v_mfma_f32_16x16x32_bf16 v[68:71], v[158:161], v[236:239], v[68:71]
	v_mfma_f32_16x16x32_bf16 v[64:67], v[166:169], v[236:239], v[64:67]
	s_setprio 0
	s_setprio 1
	v_mfma_f32_16x16x32_bf16 v[28:31], v[170:173], v[186:189], v[28:31]
	v_mfma_f32_16x16x32_bf16 v[24:27], v[178:181], v[186:189], v[24:27]
	v_mfma_f32_16x16x32_bf16 v[20:23], v[170:173], v[194:197], v[20:23]
	v_mfma_f32_16x16x32_bf16 v[16:19], v[178:181], v[194:197], v[16:19]
	v_mfma_f32_16x16x32_bf16 v[12:15], v[170:173], v[202:205], v[12:15]
	v_mfma_f32_16x16x32_bf16 v[8:11], v[178:181], v[202:205], v[8:11]
	v_mfma_f32_16x16x32_bf16 v[4:7], v[170:173], v[232:235], v[4:7]
	v_mfma_f32_16x16x32_bf16 v[0:3], v[178:181], v[232:235], v[0:3]
	v_mfma_f32_16x16x32_bf16 v[28:31], v[174:177], v[190:193], v[28:31]
	v_mfma_f32_16x16x32_bf16 v[24:27], v[182:185], v[190:193], v[24:27]
	v_mfma_f32_16x16x32_bf16 v[20:23], v[174:177], v[198:201], v[20:23]
	v_mfma_f32_16x16x32_bf16 v[16:19], v[182:185], v[198:201], v[16:19]
	v_mfma_f32_16x16x32_bf16 v[12:15], v[174:177], v[228:231], v[12:15]
	v_mfma_f32_16x16x32_bf16 v[8:11], v[182:185], v[228:231], v[8:11]
	v_mfma_f32_16x16x32_bf16 v[4:7], v[174:177], v[236:239], v[4:7]
	v_mfma_f32_16x16x32_bf16 v[0:3], v[182:185], v[236:239], v[0:3]
	s_setprio 0
	s_barrier
	s_add_i32 s60, 0, 0x18000
	v_add_u32_e32 v140, s60, v224
	s_add_i32 s61, 0, 0x1c000
	ds_read_b128 v[154:157], v140
	ds_read_b128 v[158:161], v140 offset:1024
	ds_read_b128 v[162:165], v140 offset:2048
	ds_read_b128 v[166:169], v140 offset:3072
	v_add_u32_e32 v140, s61, v224
	ds_read_b128 v[170:173], v140
	ds_read_b128 v[174:177], v140 offset:1024
	ds_read_b128 v[178:181], v140 offset:2048
	ds_read_b128 v[182:185], v140 offset:3072
	s_add_u32 s34, s34, s10
	s_addc_u32 s35, s35, 0
	s_mov_b32 m0, s44
	v_lshl_add_u64 v[248:249], s[34:35], 0, v[128:129]
	ds_read_b128 v[186:189], v226 offset:32768
	ds_read_b128 v[190:193], v226 offset:33792
	ds_read_b128 v[194:197], v226 offset:34816
	ds_read_b128 v[198:201], v226 offset:35840
	ds_read_b128 v[202:205], v226 offset:36864
	ds_read_b128 v[228:231], v226 offset:37888
	ds_read_b128 v[232:235], v226 offset:38912
	ds_read_b128 v[236:239], v226 offset:39936
	global_load_lds_dwordx4 v[248:249], off
	v_lshl_add_u64 v[248:249], s[34:35], 0, v[130:131]
	s_mov_b32 m0, s45
	s_nop 0
	global_load_lds_dwordx4 v[248:249], off
	s_waitcnt vmcnt(8)
	s_waitcnt lgkmcnt(0)
	s_barrier
	s_setprio 1
	s_waitcnt lgkmcnt(0)
	v_mfma_f32_16x16x32_bf16 v[124:127], v[154:157], v[186:189], v[124:127]
	v_mfma_f32_16x16x32_bf16 v[120:123], v[162:165], v[186:189], v[120:123]
	v_mfma_f32_16x16x32_bf16 v[116:119], v[154:157], v[194:197], v[116:119]
	v_mfma_f32_16x16x32_bf16 v[112:115], v[162:165], v[194:197], v[112:115]
	v_mfma_f32_16x16x32_bf16 v[108:111], v[154:157], v[202:205], v[108:111]
	v_mfma_f32_16x16x32_bf16 v[104:107], v[162:165], v[202:205], v[104:107]
	v_mfma_f32_16x16x32_bf16 v[100:103], v[154:157], v[232:235], v[100:103]
	v_mfma_f32_16x16x32_bf16 v[96:99], v[162:165], v[232:235], v[96:99]
	v_mfma_f32_16x16x32_bf16 v[124:127], v[158:161], v[190:193], v[124:127]
	v_mfma_f32_16x16x32_bf16 v[120:123], v[166:169], v[190:193], v[120:123]
	v_mfma_f32_16x16x32_bf16 v[116:119], v[158:161], v[198:201], v[116:119]
	v_mfma_f32_16x16x32_bf16 v[112:115], v[166:169], v[198:201], v[112:115]
	v_mfma_f32_16x16x32_bf16 v[108:111], v[158:161], v[228:231], v[108:111]
	v_mfma_f32_16x16x32_bf16 v[104:107], v[166:169], v[228:231], v[104:107]
	v_mfma_f32_16x16x32_bf16 v[100:103], v[158:161], v[236:239], v[100:103]
	v_mfma_f32_16x16x32_bf16 v[96:99], v[166:169], v[236:239], v[96:99]
	s_setprio 0
	s_setprio 1
	v_mfma_f32_16x16x32_bf16 v[60:63], v[170:173], v[186:189], v[60:63]
	v_mfma_f32_16x16x32_bf16 v[56:59], v[178:181], v[186:189], v[56:59]
	v_mfma_f32_16x16x32_bf16 v[52:55], v[170:173], v[194:197], v[52:55]
	v_mfma_f32_16x16x32_bf16 v[48:51], v[178:181], v[194:197], v[48:51]
	v_mfma_f32_16x16x32_bf16 v[44:47], v[170:173], v[202:205], v[44:47]
	v_mfma_f32_16x16x32_bf16 v[40:43], v[178:181], v[202:205], v[40:43]
	v_mfma_f32_16x16x32_bf16 v[36:39], v[170:173], v[232:235], v[36:39]
	v_mfma_f32_16x16x32_bf16 v[32:35], v[178:181], v[232:235], v[32:35]
	v_mfma_f32_16x16x32_bf16 v[60:63], v[174:177], v[190:193], v[60:63]
	v_mfma_f32_16x16x32_bf16 v[56:59], v[182:185], v[190:193], v[56:59]
	v_mfma_f32_16x16x32_bf16 v[52:55], v[174:177], v[198:201], v[52:55]
	v_mfma_f32_16x16x32_bf16 v[48:51], v[182:185], v[198:201], v[48:51]
	v_mfma_f32_16x16x32_bf16 v[44:47], v[174:177], v[228:231], v[44:47]
	v_mfma_f32_16x16x32_bf16 v[40:43], v[182:185], v[228:231], v[40:43]
	v_mfma_f32_16x16x32_bf16 v[36:39], v[174:177], v[236:239], v[36:39]
	v_mfma_f32_16x16x32_bf16 v[32:35], v[182:185], v[236:239], v[32:35]
	s_setprio 0
	s_barrier
; #define PG8_STAGE(bufoff, gbase, voff) do { _Pragma("unroll") for (int _i = 0; _i < 2; ++_i) \
;         __builtin_amdgcn_global_load_lds((const unsigned*)((const char*)(gbase) + (voff)[_i]), (PG8_LAS unsigned*)(lds + (bufoff) + ldsw + _i * 8192), 16, 0, 0); } while (0)
; #define PG8_LDA(dst, b, h) do { _Pragma("unroll") for (int m = 0; m < 4; ++m) _Pragma("unroll") for (int k = 0; k < 2; ++k) dst[m][k] = *(const PG8_LAS bf16x8*)(lds + PG8_SA(b, h) + aoff + m * 2048 + k * 1024); } while (0)
; #define PG8_MMA(ai, bj, At, Bt) do { __builtin_amdgcn_s_setprio(1); _Pragma("unroll") for (int m = 0; m < 4; ++m) _Pragma("unroll") for (int n = 0; n < 2; ++n) _Pragma("unroll") for (int k = 0; k < 2; ++k) \
;         acc[ai][bj][m][n] = __builtin_amdgcn_mfma_f32_16x16x32_bf16(Bt[n][k], At[m][k], acc[ai][bj][m][n], 0, 0, 0); __builtin_amdgcn_s_setprio(0); } while (0)
; #define PG8_WAIT_V(n) asm volatile("s_waitcnt vmcnt(" #n ")" ::: "memory")
; #define PG8_WAIT_L(n) asm volatile("s_waitcnt lgkmcnt(" #n ")" ::: "memory")
; #define PG8_BAR __builtin_amdgcn_s_barrier()
; #define PG8_SCHED __builtin_amdgcn_sched_barrier(0)
; template <class Epi, class Sched, bool ALIGN_EPI = false, bool SP2 = false>
; __device__ __forceinline__ void gemm_phase(PG8_LAS unsigned char* lds, const Gemm g, const Sched& S, const Epi& E, const int tid) {
;     ...
;         for (int t = 0; t < nt; t += 2) {
;             const bool last = (t == nt - 2);
;             const char* a1 = cA + (size_t)(t + 1) * kstep;
;             const char* a2 = last ? nA : cA + (size_t)(t + 2) * kstep; const char* b2 = last ? nB : cB + (size_t)(t + 2) * kstep;
;             const char* a3 = a2 + kstep; const char* b3 = b2 + kstep;
;     ...
;             PG8_LDA(At, 1, 1); PG8_STAGE(PG8_SB(1, 0), b3, voffB); PG8_STAGE(PG8_SB(1, 1), b3 + hstep, voffB); PG8_STAGE(PG8_SA(1, 0), a3, voffA);
;             PG8_WAIT_V(8); PG8_WAIT_L(0); PG8_BAR; PG8_MMA(1, 0, At, B0); PG8_MMA(1, 1, At, B1); PG8_BAR; PG8_SCHED;
	s_add_i32 s34, s60, s41
	v_lshl_add_u64 v[138:139], v[138:139], 0, s[68:69]
	s_mov_b32 m0, s34
	ds_read_b128 v[186:189], v226 offset:49152
	ds_read_b128 v[190:193], v226 offset:50176
	ds_read_b128 v[194:197], v226 offset:51200
	ds_read_b128 v[198:201], v226 offset:52224
	ds_read_b128 v[202:205], v226 offset:53248
	ds_read_b128 v[228:231], v226 offset:54272
	ds_read_b128 v[232:235], v226 offset:55296
	ds_read_b128 v[236:239], v226 offset:56320
	global_load_lds_dwordx4 v[138:139], off
	v_lshl_add_u64 v[138:139], v[142:143], 0, s[68:69]
	s_add_i32 m0, s34, 0x2000
	s_add_i32 s34, s61, s41
	global_load_lds_dwordx4 v[138:139], off
	v_lshl_add_u64 v[138:139], v[240:241], 0, s[68:69]
	s_mov_b32 m0, s34
	s_nop 0
	global_load_lds_dwordx4 v[138:139], off
	v_lshl_add_u64 v[138:139], v[242:243], 0, s[68:69]
	s_add_i32 m0, s34, 0x2000
	s_nop 0
	global_load_lds_dwordx4 v[138:139], off
	v_lshl_add_u64 v[138:139], v[244:245], 0, s[68:69]
	s_mov_b32 m0, s48
	s_nop 0
	global_load_lds_dwordx4 v[138:139], off
	v_lshl_add_u64 v[138:139], v[246:247], 0, s[68:69]
	s_mov_b32 m0, s49
	s_nop 0
	global_load_lds_dwordx4 v[138:139], off
	s_waitcnt vmcnt(8)
	s_waitcnt lgkmcnt(0)
	s_barrier
	s_setprio 1
	s_waitcnt lgkmcnt(0)
	v_mfma_f32_16x16x32_bf16 v[92:95], v[154:157], v[186:189], v[92:95]
	v_mfma_f32_16x16x32_bf16 v[88:91], v[162:165], v[186:189], v[88:91]
	v_mfma_f32_16x16x32_bf16 v[84:87], v[154:157], v[194:197], v[84:87]
	v_mfma_f32_16x16x32_bf16 v[80:83], v[162:165], v[194:197], v[80:83]
	v_mfma_f32_16x16x32_bf16 v[76:79], v[154:157], v[202:205], v[76:79]
	v_mfma_f32_16x16x32_bf16 v[72:75], v[162:165], v[202:205], v[72:75]
	v_mfma_f32_16x16x32_bf16 v[68:71], v[154:157], v[232:235], v[68:71]
	v_mfma_f32_16x16x32_bf16 v[64:67], v[162:165], v[232:235], v[64:67]
	v_mfma_f32_16x16x32_bf16 v[92:95], v[158:161], v[190:193], v[92:95]
	v_mfma_f32_16x16x32_bf16 v[88:91], v[166:169], v[190:193], v[88:91]
	v_mfma_f32_16x16x32_bf16 v[84:87], v[158:161], v[198:201], v[84:87]
	v_mfma_f32_16x16x32_bf16 v[80:83], v[166:169], v[198:201], v[80:83]
	v_mfma_f32_16x16x32_bf16 v[76:79], v[158:161], v[228:231], v[76:79]
	v_mfma_f32_16x16x32_bf16 v[72:75], v[166:169], v[228:231], v[72:75]
	v_mfma_f32_16x16x32_bf16 v[68:71], v[158:161], v[236:239], v[68:71]
	v_mfma_f32_16x16x32_bf16 v[64:67], v[166:169], v[236:239], v[64:67]
	s_setprio 0
	s_setprio 1
	v_mfma_f32_16x16x32_bf16 v[28:31], v[170:173], v[186:189], v[28:31]
	v_mfma_f32_16x16x32_bf16 v[24:27], v[178:181], v[186:189], v[24:27]
	v_mfma_f32_16x16x32_bf16 v[20:23], v[170:173], v[194:197], v[20:23]
	v_mfma_f32_16x16x32_bf16 v[16:19], v[178:181], v[194:197], v[16:19]
	v_mfma_f32_16x16x32_bf16 v[12:15], v[170:173], v[202:205], v[12:15]
	v_mfma_f32_16x16x32_bf16 v[8:11], v[178:181], v[202:205], v[8:11]
	v_mfma_f32_16x16x32_bf16 v[4:7], v[170:173], v[232:235], v[4:7]
	v_mfma_f32_16x16x32_bf16 v[0:3], v[178:181], v[232:235], v[0:3]
	v_mfma_f32_16x16x32_bf16 v[28:31], v[174:177], v[190:193], v[28:31]
	v_mfma_f32_16x16x32_bf16 v[24:27], v[182:185], v[190:193], v[24:27]
	v_mfma_f32_16x16x32_bf16 v[20:23], v[174:177], v[198:201], v[20:23]
	v_mfma_f32_16x16x32_bf16 v[16:19], v[182:185], v[198:201], v[16:19]
	v_mfma_f32_16x16x32_bf16 v[12:15], v[174:177], v[228:231], v[12:15]
	v_mfma_f32_16x16x32_bf16 v[8:11], v[182:185], v[228:231], v[8:11]
	v_mfma_f32_16x16x32_bf16 v[4:7], v[174:177], v[236:239], v[4:7]
	v_mfma_f32_16x16x32_bf16 v[0:3], v[182:185], v[236:239], v[0:3]
	s_setprio 0
	s_add_u32 s30, s30, 0x100
	s_addc_u32 s31, s31, 0
	s_add_u32 s57, s57, 0x100
	s_addc_u32 s58, s58, 0
	s_cmp_ge_u32 s59, s51
	s_cselect_b32 s70, 1, 0
	s_mov_b32 s34, s59
	s_add_i32 s59, s34, 2
	s_add_u32 s60, s30, 0x80
	s_addc_u32 s35, s31, 0
	s_add_i32 s62, 0, 0x10000
	s_cmp_eq_u32 s52, s34
	s_cselect_b32 s35, s3, s35
	s_cselect_b32 s34, s2, s60
	v_add_u32_e32 v138, s62, v224
	s_cselect_b32 s61, s5, s58
	s_cselect_b32 s60, s4, s57
	s_add_i32 s63, 0, 0x14000
	s_cmp_lg_u32 s70, 0
	s_barrier
	s_cbranch_scc0 .Lk881_body
	s_and_b64 vcc, exec, s[28:29]
	s_cbranch_vccz .LBB0_884
	s_barrier

; #define PG8_STAGE(bufoff, gbase, voff) do { _Pragma("unroll") for (int _i = 0; _i < 2; ++_i) \
;         __builtin_amdgcn_global_load_lds((const unsigned*)((const char*)(gbase) + (voff)[_i]), (PG8_LAS unsigned*)(lds + (bufoff) + ldsw + _i * 8192), 16, 0, 0); } while (0)
; #define PG8_LDA(dst, b, h) do { _Pragma("unroll") for (int m = 0; m < 4; ++m) _Pragma("unroll") for (int k = 0; k < 2; ++k) dst[m][k] = *(const PG8_LAS bf16x8*)(lds + PG8_SA(b, h) + aoff + m * 2048 + k * 1024); } while (0)
; #define PG8_LDB(dst, b, h) do { _Pragma("unroll") for (int n = 0; n < 2; ++n) _Pragma("unroll") for (int k = 0; k < 2; ++k) dst[n][k] = *(const PG8_LAS bf16x8*)(lds + PG8_SB(b, h) + boff + n * 2048 + k * 1024); } while (0)
; #define PG8_MMA(ai, bj, At, Bt) do { __builtin_amdgcn_s_setprio(1); _Pragma("unroll") for (int m = 0; m < 4; ++m) _Pragma("unroll") for (int n = 0; n < 2; ++n) _Pragma("unroll") for (int k = 0; k < 2; ++k) \
;         acc[ai][bj][m][n] = __builtin_amdgcn_mfma_f32_16x16x32_bf16(Bt[n][k], At[m][k], acc[ai][bj][m][n], 0, 0, 0); __builtin_amdgcn_s_setprio(0); } while (0)
; #define PG8_WAIT_V(n) asm volatile("s_waitcnt vmcnt(" #n ")" ::: "memory")
; #define PG8_WAIT_L(n) asm volatile("s_waitcnt lgkmcnt(" #n ")" ::: "memory")
; #define PG8_BAR __builtin_amdgcn_s_barrier()
; #define PG8_SCHED __builtin_amdgcn_sched_barrier(0)
; template <class Epi, class Sched, bool ALIGN_EPI = false, bool SP2 = false>
; __device__ __forceinline__ void gemm_phase(PG8_LAS unsigned char* lds, const Gemm g, const Sched& S, const Epi& E, const int tid) {
;     ...
;             if constexpr (SP2) {
;             PG8_LDB(B0, 0, 0); PG8_LDB(B1, 0, 1); PG8_SCHED; PG8_LDA(At, 0, 0); PG8_STAGE(PG8_SA(1, 1), a1 + hstep, voffA);
;             PG8_WAIT_V(8); PG8_WAIT_L(0); PG8_BAR; PG8_MMA(0, 0, At, B0); PG8_MMA(0, 1, At, B1); PG8_BAR; PG8_SCHED;
;             PG8_LDA(At, 0, 1); PG8_STAGE(PG8_SB(0, 0), b2, voffB); PG8_STAGE(PG8_SB(0, 1), b2 + hstep, voffB); PG8_STAGE(PG8_SA(0, 0), a2, voffA);
;             PG8_WAIT_V(8); PG8_WAIT_L(0); PG8_BAR; PG8_MMA(1, 0, At, B0); PG8_MMA(1, 1, At, B1); PG8_BAR; PG8_SCHED;
.Lk921_body:
	ds_read_b128 v[154:157], v138
	ds_read_b128 v[158:161], v138 offset:1024
	ds_read_b128 v[162:165], v138 offset:2048
	ds_read_b128 v[166:169], v138 offset:3072
	v_add_u32_e32 v138, s46, v141
	ds_read_b128 v[170:173], v138
	ds_read_b128 v[174:177], v138 offset:1024
	ds_read_b128 v[178:181], v138 offset:2048
	ds_read_b128 v[182:185], v138 offset:3072
	v_lshl_add_u64 v[138:139], s[16:17], 0, v[134:135]
	s_add_i32 m0, s15, 0xc000
	ds_read_b128 v[186:189], v143
	ds_read_b128 v[190:193], v143 offset:1024
	ds_read_b128 v[194:197], v143 offset:2048
	ds_read_b128 v[198:201], v143 offset:3072
	ds_read_b128 v[202:205], v143 offset:4096
	ds_read_b128 v[222:225], v143 offset:5120
	ds_read_b128 v[226:229], v143 offset:6144
	ds_read_b128 v[230:233], v143 offset:7168
	global_load_lds_dwordx4 v[138:139], off
	v_lshl_add_u64 v[138:139], s[16:17], 0, v[136:137]
	s_add_i32 m0, s15, 0xe000
	s_nop 0
	global_load_lds_dwordx4 v[138:139], off
	s_waitcnt vmcnt(8)
	s_waitcnt lgkmcnt(0)
	s_barrier
	s_setprio 1
	s_waitcnt lgkmcnt(0)
	v_mfma_f32_16x16x32_bf16 v[124:127], v[154:157], v[186:189], v[124:127]
	v_mfma_f32_16x16x32_bf16 v[120:123], v[162:165], v[186:189], v[120:123]
	v_mfma_f32_16x16x32_bf16 v[108:111], v[154:157], v[194:197], v[108:111]
	v_mfma_f32_16x16x32_bf16 v[104:107], v[162:165], v[194:197], v[104:107]
	v_mfma_f32_16x16x32_bf16 v[92:95], v[154:157], v[202:205], v[92:95]
	v_mfma_f32_16x16x32_bf16 v[88:91], v[162:165], v[202:205], v[88:91]
	v_mfma_f32_16x16x32_bf16 v[76:79], v[154:157], v[226:229], v[76:79]
	v_mfma_f32_16x16x32_bf16 v[72:75], v[162:165], v[226:229], v[72:75]
	v_mfma_f32_16x16x32_bf16 v[124:127], v[158:161], v[190:193], v[124:127]
	v_mfma_f32_16x16x32_bf16 v[120:123], v[166:169], v[190:193], v[120:123]
	v_mfma_f32_16x16x32_bf16 v[108:111], v[158:161], v[198:201], v[108:111]
	v_mfma_f32_16x16x32_bf16 v[104:107], v[166:169], v[198:201], v[104:107]
	v_mfma_f32_16x16x32_bf16 v[92:95], v[158:161], v[222:225], v[92:95]
	v_mfma_f32_16x16x32_bf16 v[88:91], v[166:169], v[222:225], v[88:91]
	v_mfma_f32_16x16x32_bf16 v[76:79], v[158:161], v[230:233], v[76:79]
	v_mfma_f32_16x16x32_bf16 v[72:75], v[166:169], v[230:233], v[72:75]
	s_setprio 0
	s_setprio 1
	v_mfma_f32_16x16x32_bf16 v[116:119], v[170:173], v[186:189], v[116:119]
	v_mfma_f32_16x16x32_bf16 v[112:115], v[178:181], v[186:189], v[112:115]
	v_mfma_f32_16x16x32_bf16 v[100:103], v[170:173], v[194:197], v[100:103]
	v_mfma_f32_16x16x32_bf16 v[96:99], v[178:181], v[194:197], v[96:99]
	v_mfma_f32_16x16x32_bf16 v[84:87], v[170:173], v[202:205], v[84:87]
	v_mfma_f32_16x16x32_bf16 v[80:83], v[178:181], v[202:205], v[80:83]
	v_mfma_f32_16x16x32_bf16 v[68:71], v[170:173], v[226:229], v[68:71]
	v_mfma_f32_16x16x32_bf16 v[64:67], v[178:181], v[226:229], v[64:67]
	v_mfma_f32_16x16x32_bf16 v[116:119], v[174:177], v[190:193], v[116:119]
	v_mfma_f32_16x16x32_bf16 v[112:115], v[182:185], v[190:193], v[112:115]
	v_mfma_f32_16x16x32_bf16 v[100:103], v[174:177], v[198:201], v[100:103]
	v_mfma_f32_16x16x32_bf16 v[96:99], v[182:185], v[198:201], v[96:99]
	v_mfma_f32_16x16x32_bf16 v[84:87], v[174:177], v[222:225], v[84:87]
	v_mfma_f32_16x16x32_bf16 v[80:83], v[182:185], v[222:225], v[80:83]
	v_mfma_f32_16x16x32_bf16 v[68:71], v[174:177], v[230:233], v[68:71]
	v_mfma_f32_16x16x32_bf16 v[64:67], v[182:185], v[230:233], v[64:67]
	s_setprio 0
	s_barrier
	s_add_i32 s43, s43, s27
	v_lshl_add_u64 v[138:139], s[18:19], 0, v[146:147]
	s_mov_b32 m0, s43
	ds_read_b128 v[186:189], v143 offset:16384
	ds_read_b128 v[190:193], v143 offset:17408
	ds_read_b128 v[194:197], v143 offset:18432
	ds_read_b128 v[198:201], v143 offset:19456
	ds_read_b128 v[202:205], v143 offset:20480
	ds_read_b128 v[222:225], v143 offset:21504
	ds_read_b128 v[226:229], v143 offset:22528
	ds_read_b128 v[230:233], v143 offset:23552
	global_load_lds_dwordx4 v[138:139], off
	s_add_i32 m0, s43, 0x2000
	s_add_u32 s44, s18, 0x40000
	v_lshl_add_u64 v[234:235], s[18:19], 0, v[132:133]
	s_addc_u32 s45, s19, 0
	s_add_i32 s43, s46, s27
	global_load_lds_dwordx4 v[234:235], off
	v_lshl_add_u64 v[236:237], s[44:45], 0, v[146:147]
	s_mov_b32 m0, s43
	v_lshl_add_u64 v[238:239], s[20:21], 0, v[130:131]
	global_load_lds_dwordx4 v[236:237], off
	v_lshl_add_u64 v[236:237], s[44:45], 0, v[132:133]
	s_add_i32 m0, s43, 0x2000
	s_nop 0
	global_load_lds_dwordx4 v[236:237], off
	v_lshl_add_u64 v[236:237], s[20:21], 0, v[128:129]
	s_mov_b32 m0, s15
	s_nop 0
	global_load_lds_dwordx4 v[236:237], off
	s_mov_b32 m0, s29
	s_nop 0
	global_load_lds_dwordx4 v[238:239], off
	s_waitcnt vmcnt(8)
	s_waitcnt lgkmcnt(0)
	s_barrier
; #define PG8_STAGE(bufoff, gbase, voff) do { _Pragma("unroll") for (int _i = 0; _i < 2; ++_i) \
;         __builtin_amdgcn_global_load_lds((const unsigned*)((const char*)(gbase) + (voff)[_i]), (PG8_LAS unsigned*)(lds + (bufoff) + ldsw + _i * 8192), 16, 0, 0); } while (0)
; #define PG8_LDA(dst, b, h) do { _Pragma("unroll") for (int m = 0; m < 4; ++m) _Pragma("unroll") for (int k = 0; k < 2; ++k) dst[m][k] = *(const PG8_LAS bf16x8*)(lds + PG8_SA(b, h) + aoff + m * 2048 + k * 1024); } while (0)
; #define PG8_LDB(dst, b, h) do { _Pragma("unroll") for (int n = 0; n < 2; ++n) _Pragma("unroll") for (int k = 0; k < 2; ++k) dst[n][k] = *(const PG8_LAS bf16x8*)(lds + PG8_SB(b, h) + boff + n * 2048 + k * 1024); } while (0)
; #define PG8_MMA(ai, bj, At, Bt) do { __builtin_amdgcn_s_setprio(1); _Pragma("unroll") for (int m = 0; m < 4; ++m) _Pragma("unroll") for (int n = 0; n < 2; ++n) _Pragma("unroll") for (int k = 0; k < 2; ++k) \
;         acc[ai][bj][m][n] = __builtin_amdgcn_mfma_f32_16x16x32_bf16(Bt[n][k], At[m][k], acc[ai][bj][m][n], 0, 0, 0); __builtin_amdgcn_s_setprio(0); } while (0)
; #define PG8_WAIT_V(n) asm volatile("s_waitcnt vmcnt(" #n ")" ::: "memory")
; #define PG8_WAIT_L(n) asm volatile("s_waitcnt lgkmcnt(" #n ")" ::: "memory")
; #define PG8_BAR __builtin_amdgcn_s_barrier()
; #define PG8_SCHED __builtin_amdgcn_sched_barrier(0)
; template <class Epi, class Sched, bool ALIGN_EPI = false, bool SP2 = false>
; __device__ __forceinline__ void gemm_phase(PG8_LAS unsigned char* lds, const Gemm g, const Sched& S, const Epi& E, const int tid) {
;     ...
;             PG8_WAIT_V(8); PG8_WAIT_L(0); PG8_BAR; PG8_MMA(1, 0, At, B0); PG8_MMA(1, 1, At, B1); PG8_BAR; PG8_SCHED;
;             PG8_LDB(B0, 1, 0); PG8_LDB(B1, 1, 1); PG8_SCHED; PG8_LDA(At, 1, 0); PG8_STAGE(PG8_SA(0, 1), a2 + hstep, voffA);
;             PG8_WAIT_V(8); PG8_WAIT_L(0); PG8_BAR; PG8_MMA(0, 0, At, B0); PG8_MMA(0, 1, At, B1); PG8_BAR; PG8_SCHED;
	s_setprio 1
	s_waitcnt lgkmcnt(0)
	v_mfma_f32_16x16x32_bf16 v[60:63], v[154:157], v[186:189], v[60:63]
	v_mfma_f32_16x16x32_bf16 v[56:59], v[162:165], v[186:189], v[56:59]
	v_mfma_f32_16x16x32_bf16 v[44:47], v[154:157], v[194:197], v[44:47]
	v_mfma_f32_16x16x32_bf16 v[40:43], v[162:165], v[194:197], v[40:43]
	v_mfma_f32_16x16x32_bf16 v[28:31], v[154:157], v[202:205], v[28:31]
	v_mfma_f32_16x16x32_bf16 v[24:27], v[162:165], v[202:205], v[24:27]
	v_mfma_f32_16x16x32_bf16 v[12:15], v[154:157], v[226:229], v[12:15]
	v_mfma_f32_16x16x32_bf16 v[4:7], v[162:165], v[226:229], v[4:7]
	v_mfma_f32_16x16x32_bf16 v[60:63], v[158:161], v[190:193], v[60:63]
	v_mfma_f32_16x16x32_bf16 v[56:59], v[166:169], v[190:193], v[56:59]
	v_mfma_f32_16x16x32_bf16 v[44:47], v[158:161], v[198:201], v[44:47]
	v_mfma_f32_16x16x32_bf16 v[40:43], v[166:169], v[198:201], v[40:43]
	v_mfma_f32_16x16x32_bf16 v[28:31], v[158:161], v[222:225], v[28:31]
	v_mfma_f32_16x16x32_bf16 v[24:27], v[166:169], v[222:225], v[24:27]
	v_mfma_f32_16x16x32_bf16 v[12:15], v[158:161], v[230:233], v[12:15]
	v_mfma_f32_16x16x32_bf16 v[4:7], v[166:169], v[230:233], v[4:7]
	s_setprio 0
	s_setprio 1
	v_mfma_f32_16x16x32_bf16 v[52:55], v[170:173], v[186:189], v[52:55]
	v_mfma_f32_16x16x32_bf16 v[48:51], v[178:181], v[186:189], v[48:51]
	v_mfma_f32_16x16x32_bf16 v[36:39], v[170:173], v[194:197], v[36:39]
	v_mfma_f32_16x16x32_bf16 v[32:35], v[178:181], v[194:197], v[32:35]
	v_mfma_f32_16x16x32_bf16 v[20:23], v[170:173], v[202:205], v[20:23]
	v_mfma_f32_16x16x32_bf16 v[16:19], v[178:181], v[202:205], v[16:19]
	v_mfma_f32_16x16x32_bf16 v[8:11], v[170:173], v[226:229], v[8:11]
	v_mfma_f32_16x16x32_bf16 v[0:3], v[178:181], v[226:229], v[0:3]
	v_mfma_f32_16x16x32_bf16 v[52:55], v[174:177], v[190:193], v[52:55]
	v_mfma_f32_16x16x32_bf16 v[48:51], v[182:185], v[190:193], v[48:51]
	v_mfma_f32_16x16x32_bf16 v[36:39], v[174:177], v[198:201], v[36:39]
	v_mfma_f32_16x16x32_bf16 v[32:35], v[182:185], v[198:201], v[32:35]
	v_mfma_f32_16x16x32_bf16 v[20:23], v[174:177], v[222:225], v[20:23]
	v_mfma_f32_16x16x32_bf16 v[16:19], v[182:185], v[222:225], v[16:19]
	v_mfma_f32_16x16x32_bf16 v[8:11], v[174:177], v[230:233], v[8:11]
	v_mfma_f32_16x16x32_bf16 v[0:3], v[182:185], v[230:233], v[0:3]
	s_setprio 0
	s_barrier
	s_add_i32 s43, 0, 0x18000
	v_add_u32_e32 v150, s43, v141
	s_add_i32 s44, 0, 0x1c000
	ds_read_b128 v[154:157], v150
	ds_read_b128 v[158:161], v150 offset:1024
	ds_read_b128 v[162:165], v150 offset:2048
	ds_read_b128 v[166:169], v150 offset:3072
	v_add_u32_e32 v150, s44, v141
	ds_read_b128 v[170:173], v150
	ds_read_b128 v[174:177], v150 offset:1024
	ds_read_b128 v[178:181], v150 offset:2048
	ds_read_b128 v[182:185], v150 offset:3072
	s_add_u32 s20, s20, 0x40000
	s_addc_u32 s21, s21, 0
	s_mov_b32 m0, s30
	v_lshl_add_u64 v[240:241], s[20:21], 0, v[128:129]
	ds_read_b128 v[186:189], v143 offset:32768
	ds_read_b128 v[190:193], v143 offset:33792
	ds_read_b128 v[194:197], v143 offset:34816
	ds_read_b128 v[198:201], v143 offset:35840
	ds_read_b128 v[202:205], v143 offset:36864
	ds_read_b128 v[222:225], v143 offset:37888
	ds_read_b128 v[226:229], v143 offset:38912
	ds_read_b128 v[230:233], v143 offset:39936
	global_load_lds_dwordx4 v[240:241], off
	v_lshl_add_u64 v[240:241], s[20:21], 0, v[130:131]
	s_mov_b32 m0, s31
	s_nop 0
	global_load_lds_dwordx4 v[240:241], off
	s_waitcnt vmcnt(8)
	s_waitcnt lgkmcnt(0)
	s_barrier
	s_setprio 1
	s_waitcnt lgkmcnt(0)
	v_mfma_f32_16x16x32_bf16 v[124:127], v[154:157], v[186:189], v[124:127]
	v_mfma_f32_16x16x32_bf16 v[120:123], v[162:165], v[186:189], v[120:123]
	v_mfma_f32_16x16x32_bf16 v[108:111], v[154:157], v[194:197], v[108:111]
	v_mfma_f32_16x16x32_bf16 v[104:107], v[162:165], v[194:197], v[104:107]
	v_mfma_f32_16x16x32_bf16 v[92:95], v[154:157], v[202:205], v[92:95]
	v_mfma_f32_16x16x32_bf16 v[88:91], v[162:165], v[202:205], v[88:91]
	v_mfma_f32_16x16x32_bf16 v[76:79], v[154:157], v[226:229], v[76:79]
	v_mfma_f32_16x16x32_bf16 v[72:75], v[162:165], v[226:229], v[72:75]
	v_mfma_f32_16x16x32_bf16 v[124:127], v[158:161], v[190:193], v[124:127]
	v_mfma_f32_16x16x32_bf16 v[120:123], v[166:169], v[190:193], v[120:123]
	v_mfma_f32_16x16x32_bf16 v[108:111], v[158:161], v[198:201], v[108:111]
	v_mfma_f32_16x16x32_bf16 v[104:107], v[166:169], v[198:201], v[104:107]
	v_mfma_f32_16x16x32_bf16 v[92:95], v[158:161], v[222:225], v[92:95]
	v_mfma_f32_16x16x32_bf16 v[88:91], v[166:169], v[222:225], v[88:91]
	v_mfma_f32_16x16x32_bf16 v[76:79], v[158:161], v[230:233], v[76:79]
	v_mfma_f32_16x16x32_bf16 v[72:75], v[166:169], v[230:233], v[72:75]
	s_setprio 0
	s_setprio 1
	v_mfma_f32_16x16x32_bf16 v[116:119], v[170:173], v[186:189], v[116:119]
	v_mfma_f32_16x16x32_bf16 v[112:115], v[178:181], v[186:189], v[112:115]
	v_mfma_f32_16x16x32_bf16 v[100:103], v[170:173], v[194:197], v[100:103]
	v_mfma_f32_16x16x32_bf16 v[96:99], v[178:181], v[194:197], v[96:99]
	v_mfma_f32_16x16x32_bf16 v[84:87], v[170:173], v[202:205], v[84:87]
	v_mfma_f32_16x16x32_bf16 v[80:83], v[178:181], v[202:205], v[80:83]
	v_mfma_f32_16x16x32_bf16 v[68:71], v[170:173], v[226:229], v[68:71]
	v_mfma_f32_16x16x32_bf16 v[64:67], v[178:181], v[226:229], v[64:67]
	v_mfma_f32_16x16x32_bf16 v[116:119], v[174:177], v[190:193], v[116:119]
	v_mfma_f32_16x16x32_bf16 v[112:115], v[182:185], v[190:193], v[112:115]
	v_mfma_f32_16x16x32_bf16 v[100:103], v[174:177], v[198:201], v[100:103]
	v_mfma_f32_16x16x32_bf16 v[96:99], v[182:185], v[198:201], v[96:99]
	v_mfma_f32_16x16x32_bf16 v[84:87], v[174:177], v[222:225], v[84:87]
	v_mfma_f32_16x16x32_bf16 v[80:83], v[182:185], v[222:225], v[80:83]
	v_mfma_f32_16x16x32_bf16 v[68:71], v[174:177], v[230:233], v[68:71]
	v_mfma_f32_16x16x32_bf16 v[64:67], v[182:185], v[230:233], v[64:67]
	s_setprio 0
	s_barrier
; #define PG8_STAGE(bufoff, gbase, voff) do { _Pragma("unroll") for (int _i = 0; _i < 2; ++_i) \
;         __builtin_amdgcn_global_load_lds((const unsigned*)((const char*)(gbase) + (voff)[_i]), (PG8_LAS unsigned*)(lds + (bufoff) + ldsw + _i * 8192), 16, 0, 0); } while (0)
; #define PG8_LDA(dst, b, h) do { _Pragma("unroll") for (int m = 0; m < 4; ++m) _Pragma("unroll") for (int k = 0; k < 2; ++k) dst[m][k] = *(const PG8_LAS bf16x8*)(lds + PG8_SA(b, h) + aoff + m * 2048 + k * 1024); } while (0)
; #define PG8_MMA(ai, bj, At, Bt) do { __builtin_amdgcn_s_setprio(1); _Pragma("unroll") for (int m = 0; m < 4; ++m) _Pragma("unroll") for (int n = 0; n < 2; ++n) _Pragma("unroll") for (int k = 0; k < 2; ++k) \
;         acc[ai][bj][m][n] = __builtin_amdgcn_mfma_f32_16x16x32_bf16(Bt[n][k], At[m][k], acc[ai][bj][m][n], 0, 0, 0); __builtin_amdgcn_s_setprio(0); } while (0)
; #define PG8_WAIT_V(n) asm volatile("s_waitcnt vmcnt(" #n ")" ::: "memory")
; #define PG8_WAIT_L(n) asm volatile("s_waitcnt lgkmcnt(" #n ")" ::: "memory")
; #define PG8_BAR __builtin_amdgcn_s_barrier()
; #define PG8_SCHED __builtin_amdgcn_sched_barrier(0)
; template <class Epi, class Sched, bool ALIGN_EPI = false, bool SP2 = false>
; __device__ __forceinline__ void gemm_phase(PG8_LAS unsigned char* lds, const Gemm g, const Sched& S, const Epi& E, const int tid) {
;     ...
;         for (int t = 0; t < nt; t += 2) {
;             const bool last = (t == nt - 2);
;             const char* a1 = cA + (size_t)(t + 1) * kstep;
;             const char* a2 = last ? nA : cA + (size_t)(t + 2) * kstep; const char* b2 = last ? nB : cB + (size_t)(t + 2) * kstep;
;             const char* a3 = a2 + kstep; const char* b3 = b2 + kstep;
;     ...
;             PG8_LDA(At, 1, 1); PG8_STAGE(PG8_SB(1, 0), b3, voffB); PG8_STAGE(PG8_SB(1, 1), b3 + hstep, voffB); PG8_STAGE(PG8_SA(1, 0), a3, voffA);
;             PG8_WAIT_V(8); PG8_WAIT_L(0); PG8_BAR; PG8_MMA(1, 0, At, B0); PG8_MMA(1, 1, At, B1); PG8_BAR; PG8_SCHED;
	s_add_i32 s20, s43, s27
	v_lshl_add_u64 v[138:139], v[138:139], 0, s[48:49]
	s_mov_b32 m0, s20
	ds_read_b128 v[186:189], v143 offset:49152
	ds_read_b128 v[190:193], v143 offset:50176
	ds_read_b128 v[194:197], v143 offset:51200
	ds_read_b128 v[198:201], v143 offset:52224
	ds_read_b128 v[202:205], v143 offset:53248
	ds_read_b128 v[222:225], v143 offset:54272
	ds_read_b128 v[226:229], v143 offset:55296
	ds_read_b128 v[230:233], v143 offset:56320
	global_load_lds_dwordx4 v[138:139], off
	s_add_i32 m0, s20, 0x2000
	s_add_u32 s18, s18, 0x40080
	v_lshl_add_u64 v[138:139], v[234:235], 0, s[48:49]
	s_addc_u32 s19, s19, 0
	s_add_i32 s20, s44, s27
	global_load_lds_dwordx4 v[138:139], off
	v_lshl_add_u64 v[138:139], s[18:19], 0, v[146:147]
	s_mov_b32 m0, s20
	s_nop 0
	global_load_lds_dwordx4 v[138:139], off
	v_lshl_add_u64 v[138:139], s[18:19], 0, v[132:133]
	s_add_i32 m0, s20, 0x2000
	s_nop 0
	global_load_lds_dwordx4 v[138:139], off
	v_lshl_add_u64 v[138:139], v[236:237], 0, s[48:49]
	s_mov_b32 m0, s34
	s_nop 0
	global_load_lds_dwordx4 v[138:139], off
	v_lshl_add_u64 v[138:139], v[238:239], 0, s[48:49]
	s_mov_b32 m0, s35
	s_nop 0
	global_load_lds_dwordx4 v[138:139], off
	s_waitcnt vmcnt(8)
	s_waitcnt lgkmcnt(0)
	s_barrier
	s_setprio 1
	s_waitcnt lgkmcnt(0)
	v_mfma_f32_16x16x32_bf16 v[60:63], v[154:157], v[186:189], v[60:63]
	v_mfma_f32_16x16x32_bf16 v[56:59], v[162:165], v[186:189], v[56:59]
	v_mfma_f32_16x16x32_bf16 v[44:47], v[154:157], v[194:197], v[44:47]
	v_mfma_f32_16x16x32_bf16 v[40:43], v[162:165], v[194:197], v[40:43]
	v_mfma_f32_16x16x32_bf16 v[28:31], v[154:157], v[202:205], v[28:31]
	v_mfma_f32_16x16x32_bf16 v[24:27], v[162:165], v[202:205], v[24:27]
	v_mfma_f32_16x16x32_bf16 v[12:15], v[154:157], v[226:229], v[12:15]
	v_mfma_f32_16x16x32_bf16 v[4:7], v[162:165], v[226:229], v[4:7]
	v_mfma_f32_16x16x32_bf16 v[60:63], v[158:161], v[190:193], v[60:63]
	v_mfma_f32_16x16x32_bf16 v[56:59], v[166:169], v[190:193], v[56:59]
	v_mfma_f32_16x16x32_bf16 v[44:47], v[158:161], v[198:201], v[44:47]
	v_mfma_f32_16x16x32_bf16 v[40:43], v[166:169], v[198:201], v[40:43]
	v_mfma_f32_16x16x32_bf16 v[28:31], v[158:161], v[222:225], v[28:31]
	v_mfma_f32_16x16x32_bf16 v[24:27], v[166:169], v[222:225], v[24:27]
	v_mfma_f32_16x16x32_bf16 v[12:15], v[158:161], v[230:233], v[12:15]
	v_mfma_f32_16x16x32_bf16 v[4:7], v[166:169], v[230:233], v[4:7]
	s_setprio 0
	s_setprio 1
	v_mfma_f32_16x16x32_bf16 v[52:55], v[170:173], v[186:189], v[52:55]
	v_mfma_f32_16x16x32_bf16 v[48:51], v[178:181], v[186:189], v[48:51]
	v_mfma_f32_16x16x32_bf16 v[36:39], v[170:173], v[194:197], v[36:39]
	v_mfma_f32_16x16x32_bf16 v[32:35], v[178:181], v[194:197], v[32:35]
	v_mfma_f32_16x16x32_bf16 v[20:23], v[170:173], v[202:205], v[20:23]
	v_mfma_f32_16x16x32_bf16 v[16:19], v[178:181], v[202:205], v[16:19]
	v_mfma_f32_16x16x32_bf16 v[8:11], v[170:173], v[226:229], v[8:11]
	v_mfma_f32_16x16x32_bf16 v[0:3], v[178:181], v[226:229], v[0:3]
	v_mfma_f32_16x16x32_bf16 v[52:55], v[174:177], v[190:193], v[52:55]
	v_mfma_f32_16x16x32_bf16 v[48:51], v[182:185], v[190:193], v[48:51]
	v_mfma_f32_16x16x32_bf16 v[36:39], v[174:177], v[198:201], v[36:39]
	v_mfma_f32_16x16x32_bf16 v[32:35], v[182:185], v[198:201], v[32:35]
	v_mfma_f32_16x16x32_bf16 v[20:23], v[174:177], v[222:225], v[20:23]
	v_mfma_f32_16x16x32_bf16 v[16:19], v[182:185], v[222:225], v[16:19]
	v_mfma_f32_16x16x32_bf16 v[8:11], v[174:177], v[230:233], v[8:11]
	v_mfma_f32_16x16x32_bf16 v[0:3], v[182:185], v[230:233], v[0:3]
	s_setprio 0
	s_add_i32 s42, s42, 2
	s_add_u32 s16, s16, 0x100
	s_addc_u32 s17, s17, 0
	s_add_u32 s40, s40, 0x100
	s_addc_u32 s41, s41, 0
	s_add_u32 s18, s16, 0xfffc0080
	s_addc_u32 s19, s17, -1
	s_add_i32 s43, 0, 0x10000
	s_cmp_eq_u32 s42, 12
	s_cselect_b32 s21, s9, s19
	s_cselect_b32 s20, s38, s18
	v_add_u32_e32 v138, s43, v141
	s_cselect_b32 s19, s7, s41
	s_cselect_b32 s18, s39, s40
	s_add_i32 s46, 0, 0x14000
	s_cmp_gt_u32 s42, 13
	s_barrier
	s_cbranch_scc0 .Lk921_body
	s_and_b64 vcc, exec, s[4:5]
	s_cbranch_vccz .LBB0_924
	s_barrier
